# epires-gemms-unit-setup-wait-only-for-loads
# speedup vs baseline: 1.0107x; 1.0018x over previous
; template <class Epi>
; __device__ __forceinline__ void gemm_phase(LAS unsigned char* lds, const Gemm g, const StaticOrder& S, const Epi& E) {
;     ...
;         const bool has_next = S.next(ui + 1, nxt);
;         const char* nA = has_next ? (const char*)g.A + (size_t)nxt.pm * tstepA + (size_t)(nxt.pn >> g.gshift) * g.gstride : cA;
;         const char* nB = has_next ? (const char*)g.Bt + (size_t)nxt.pn * tstepB : cB;
;     ...
; #pragma unroll
;         for (int a = 0; a < 2; ++a)
; #pragma unroll
;             for (int b = 0; b < 2; ++b)
; #pragma unroll
;                 for (int m = 0; m < 4; ++m)
; #pragma unroll
;                     for (int n = 0; n < 2; ++n) acc[a][b][m][n] = (f32x4){0.f, 0.f, 0.f, 0.f};
;         cur = nxt; cA = nA; cB = nB; ++ui;
.LBB0_292:
	s_ashr_i32 s47, s46, 31
	s_lshl_b64 s[0:1], s[46:47], 20
	s_add_u32 s45, s57, s0
	s_addc_u32 s47, s58, s1
	s_ashr_i32 s0, s44, 1
	s_ashr_i32 s1, s0, 31
	s_lshl_b64 s[0:1], s[0:1], 17
	v_cmp_lt_i64_e32 vcc, s[48:49], v[194:195]
	s_add_u32 s48, s45, s0
	s_addc_u32 s49, s47, s1
	s_and_b64 s[0:1], vcc, exec
	s_cselect_b32 s0, s49, s9
	s_cselect_b32 s1, s48, s8
	s_ashr_i32 s45, s44, 31
	s_lshl_b64 s[50:51], s[44:45], 18
	s_add_u32 s50, s34, s50
	s_addc_u32 s51, s35, s51
	s_and_b64 s[54:55], vcc, exec
	s_cselect_b32 s45, s51, s53
	s_cselect_b32 s47, s50, s52
	s_add_u32 s93, s52, 0x8000
	v_mov_b32_e32 v0, 0
	s_addc_u32 s94, s53, 0
	s_mov_b32 s95, -2
	v_mov_b32_e32 v1, v0
	v_mov_b32_e32 v2, v0
	v_mov_b32_e32 v3, v0
	s_waitcnt vmcnt(8)
	v_mov_b32_e32 v4, v0
	v_mov_b32_e32 v5, v0
	v_mov_b32_e32 v6, v0
	v_mov_b32_e32 v7, v0
	v_mov_b32_e32 v12, v0
	v_mov_b32_e32 v13, v0
	v_mov_b32_e32 v14, v0
	v_mov_b32_e32 v15, v0
	v_mov_b32_e32 v20, v0
	v_mov_b32_e32 v21, v0
	v_mov_b32_e32 v22, v0
	v_mov_b32_e32 v23, v0
	v_mov_b32_e32 v28, v0
	v_mov_b32_e32 v29, v0
	v_mov_b32_e32 v30, v0
	v_mov_b32_e32 v31, v0
	v_mov_b32_e32 v36, v0
	v_mov_b32_e32 v37, v0
	v_mov_b32_e32 v38, v0
	v_mov_b32_e32 v39, v0
	v_mov_b32_e32 v44, v0
	v_mov_b32_e32 v45, v0
	v_mov_b32_e32 v46, v0
	v_mov_b32_e32 v47, v0
	v_mov_b32_e32 v52, v0
	v_mov_b32_e32 v53, v0
	v_mov_b32_e32 v54, v0
	v_mov_b32_e32 v55, v0
	v_mov_b32_e32 v8, v0
	v_mov_b32_e32 v9, v0
	v_mov_b32_e32 v10, v0
	v_mov_b32_e32 v11, v0
	v_mov_b32_e32 v16, v0
	v_mov_b32_e32 v17, v0
	v_mov_b32_e32 v18, v0
	v_mov_b32_e32 v19, v0
	v_mov_b32_e32 v24, v0
	v_mov_b32_e32 v25, v0
	v_mov_b32_e32 v26, v0
	v_mov_b32_e32 v27, v0
	v_mov_b32_e32 v32, v0
	v_mov_b32_e32 v33, v0
	v_mov_b32_e32 v34, v0
	v_mov_b32_e32 v35, v0
	v_mov_b32_e32 v40, v0
	v_mov_b32_e32 v41, v0
	v_mov_b32_e32 v42, v0
	v_mov_b32_e32 v43, v0
	v_mov_b32_e32 v48, v0
	v_mov_b32_e32 v49, v0
	v_mov_b32_e32 v50, v0
	v_mov_b32_e32 v51, v0
	v_mov_b32_e32 v56, v0
	v_mov_b32_e32 v57, v0
	v_mov_b32_e32 v58, v0
	v_mov_b32_e32 v59, v0
	v_mov_b32_e32 v60, v0
	v_mov_b32_e32 v61, v0
	v_mov_b32_e32 v62, v0
	v_mov_b32_e32 v63, v0
	v_mov_b32_e32 v64, v0
	v_mov_b32_e32 v65, v0
	v_mov_b32_e32 v66, v0
	v_mov_b32_e32 v67, v0
	v_mov_b32_e32 v68, v0
	v_mov_b32_e32 v69, v0
	v_mov_b32_e32 v70, v0
	v_mov_b32_e32 v71, v0
	v_mov_b32_e32 v76, v0
	v_mov_b32_e32 v77, v0
	v_mov_b32_e32 v78, v0
	v_mov_b32_e32 v79, v0
	v_mov_b32_e32 v84, v0
	v_mov_b32_e32 v85, v0
	v_mov_b32_e32 v86, v0
	v_mov_b32_e32 v87, v0
	v_mov_b32_e32 v92, v0
	v_mov_b32_e32 v93, v0
	v_mov_b32_e32 v94, v0
	v_mov_b32_e32 v95, v0
	v_mov_b32_e32 v100, v0
	v_mov_b32_e32 v101, v0
	v_mov_b32_e32 v102, v0
	v_mov_b32_e32 v103, v0
	v_mov_b32_e32 v104, v0
	v_mov_b32_e32 v105, v0
	v_mov_b32_e32 v106, v0
	v_mov_b32_e32 v107, v0
	v_mov_b32_e32 v108, v0
	v_mov_b32_e32 v109, v0
	v_mov_b32_e32 v110, v0
	v_mov_b32_e32 v111, v0
	v_mov_b32_e32 v72, v0
	v_mov_b32_e32 v73, v0
	v_mov_b32_e32 v74, v0
	v_mov_b32_e32 v75, v0
	v_mov_b32_e32 v80, v0
	v_mov_b32_e32 v81, v0
	v_mov_b32_e32 v82, v0
	v_mov_b32_e32 v83, v0
	v_mov_b32_e32 v88, v0
	v_mov_b32_e32 v89, v0
	v_mov_b32_e32 v90, v0
	v_mov_b32_e32 v91, v0
	v_mov_b32_e32 v96, v0
	v_mov_b32_e32 v97, v0
	v_mov_b32_e32 v98, v0
	v_mov_b32_e32 v99, v0
	v_mov_b32_e32 v112, v0
	v_mov_b32_e32 v113, v0
	v_mov_b32_e32 v114, v0
	v_mov_b32_e32 v115, v0
	v_mov_b32_e32 v116, v0
	v_mov_b32_e32 v117, v0
	v_mov_b32_e32 v118, v0
	v_mov_b32_e32 v119, v0
	v_mov_b32_e32 v120, v0
	v_mov_b32_e32 v121, v0
	v_mov_b32_e32 v122, v0
	v_mov_b32_e32 v123, v0
	v_mov_b32_e32 v124, v0
	v_mov_b32_e32 v125, v0
	v_mov_b32_e32 v126, v0
	v_mov_b32_e32 v127, v0

; template <class Epi>
; __device__ __forceinline__ void gemm_phase(LAS unsigned char* lds, const Gemm g, const StaticOrder& S, const Epi& E) {
;     ...
;         const bool has_next = S.next(ui + 1, nxt);
;         const char* nA = has_next ? (const char*)g.A + (size_t)nxt.pm * tstepA + (size_t)(nxt.pn >> g.gshift) * g.gstride : cA;
;         const char* nB = has_next ? (const char*)g.Bt + (size_t)nxt.pn * tstepB : cB;
;     ...
; #pragma unroll
;         for (int a = 0; a < 2; ++a)
; #pragma unroll
;             for (int b = 0; b < 2; ++b)
; #pragma unroll
;                 for (int m = 0; m < 4; ++m)
; #pragma unroll
;                     for (int n = 0; n < 2; ++n) acc[a][b][m][n] = (f32x4){0.f, 0.f, 0.f, 0.f};
;         cur = nxt; cA = nA; cB = nB; ++ui;
.LBB0_609:
	s_ashr_i32 s55, s54, 31
	s_lshl_b64 s[0:1], s[54:55], 20
	v_cmp_lt_i64_e32 vcc, s[56:57], v[192:193]
	s_add_u32 s56, s6, s0
	s_addc_u32 s57, s7, s1
	s_and_b64 s[0:1], vcc, exec
	s_cselect_b32 s0, s57, s61
	s_cselect_b32 s1, s56, s60
	s_ashr_i32 s53, s52, 31
	s_lshl_b64 s[48:49], s[52:53], 20
	s_add_u32 s58, s17, s48
	s_addc_u32 s59, s21, s49
	s_and_b64 s[48:49], vcc, exec
	s_cselect_b32 s53, s59, s63
	s_cselect_b32 s55, s58, s62
	s_add_u32 s69, s62, 0x8000
	v_mov_b32_e32 v0, 0
	s_addc_u32 s70, s63, 0
	s_mov_b32 s71, -2
	v_mov_b32_e32 v1, v0
	v_mov_b32_e32 v2, v0
	v_mov_b32_e32 v3, v0
	s_waitcnt vmcnt(16)
	v_mov_b32_e32 v4, v0
	v_mov_b32_e32 v5, v0
	v_mov_b32_e32 v6, v0
	v_mov_b32_e32 v7, v0
	v_mov_b32_e32 v16, v0
	v_mov_b32_e32 v17, v0
	v_mov_b32_e32 v18, v0
	v_mov_b32_e32 v19, v0
	v_mov_b32_e32 v20, v0
	v_mov_b32_e32 v21, v0
	v_mov_b32_e32 v22, v0
	v_mov_b32_e32 v23, v0
	v_mov_b32_e32 v32, v0
	v_mov_b32_e32 v33, v0
	v_mov_b32_e32 v34, v0
	v_mov_b32_e32 v35, v0
	v_mov_b32_e32 v36, v0
	v_mov_b32_e32 v37, v0
	v_mov_b32_e32 v38, v0
	v_mov_b32_e32 v39, v0
	v_mov_b32_e32 v48, v0
	v_mov_b32_e32 v49, v0
	v_mov_b32_e32 v50, v0
	v_mov_b32_e32 v51, v0
	v_mov_b32_e32 v52, v0
	v_mov_b32_e32 v53, v0
	v_mov_b32_e32 v54, v0
	v_mov_b32_e32 v55, v0
	v_mov_b32_e32 v8, v0
	v_mov_b32_e32 v9, v0
	v_mov_b32_e32 v10, v0
	v_mov_b32_e32 v11, v0
	v_mov_b32_e32 v12, v0
	v_mov_b32_e32 v13, v0
	v_mov_b32_e32 v14, v0
	v_mov_b32_e32 v15, v0
	v_mov_b32_e32 v24, v0
	v_mov_b32_e32 v25, v0
	v_mov_b32_e32 v26, v0
	v_mov_b32_e32 v27, v0
	v_mov_b32_e32 v28, v0
	v_mov_b32_e32 v29, v0
	v_mov_b32_e32 v30, v0
	v_mov_b32_e32 v31, v0
	v_mov_b32_e32 v40, v0
	v_mov_b32_e32 v41, v0
	v_mov_b32_e32 v42, v0
	v_mov_b32_e32 v43, v0
	v_mov_b32_e32 v44, v0
	v_mov_b32_e32 v45, v0
	v_mov_b32_e32 v46, v0
	v_mov_b32_e32 v47, v0
	v_mov_b32_e32 v56, v0
	v_mov_b32_e32 v57, v0
	v_mov_b32_e32 v58, v0
	v_mov_b32_e32 v59, v0
	v_mov_b32_e32 v60, v0
	v_mov_b32_e32 v61, v0
	v_mov_b32_e32 v62, v0
	v_mov_b32_e32 v63, v0
	v_mov_b32_e32 v64, v0
	v_mov_b32_e32 v65, v0
	v_mov_b32_e32 v66, v0
	v_mov_b32_e32 v67, v0
	v_mov_b32_e32 v68, v0
	v_mov_b32_e32 v69, v0
	v_mov_b32_e32 v70, v0
	v_mov_b32_e32 v71, v0
	v_mov_b32_e32 v80, v0
	v_mov_b32_e32 v81, v0
	v_mov_b32_e32 v82, v0
	v_mov_b32_e32 v83, v0
	v_mov_b32_e32 v84, v0
	v_mov_b32_e32 v85, v0
	v_mov_b32_e32 v86, v0
	v_mov_b32_e32 v87, v0
	v_mov_b32_e32 v96, v0
	v_mov_b32_e32 v97, v0
	v_mov_b32_e32 v98, v0
	v_mov_b32_e32 v99, v0
	v_mov_b32_e32 v100, v0
	v_mov_b32_e32 v101, v0
	v_mov_b32_e32 v102, v0
	v_mov_b32_e32 v103, v0
	v_mov_b32_e32 v112, v0
	v_mov_b32_e32 v113, v0
	v_mov_b32_e32 v114, v0
	v_mov_b32_e32 v115, v0
	v_mov_b32_e32 v116, v0
	v_mov_b32_e32 v117, v0
	v_mov_b32_e32 v118, v0
	v_mov_b32_e32 v119, v0
	v_mov_b32_e32 v72, v0
	v_mov_b32_e32 v73, v0
	v_mov_b32_e32 v74, v0
	v_mov_b32_e32 v75, v0
	v_mov_b32_e32 v76, v0
	v_mov_b32_e32 v77, v0
	v_mov_b32_e32 v78, v0
	v_mov_b32_e32 v79, v0
	v_mov_b32_e32 v88, v0
	v_mov_b32_e32 v89, v0
	v_mov_b32_e32 v90, v0
	v_mov_b32_e32 v91, v0
	v_mov_b32_e32 v92, v0
	v_mov_b32_e32 v93, v0
	v_mov_b32_e32 v94, v0
	v_mov_b32_e32 v95, v0
	v_mov_b32_e32 v104, v0
	v_mov_b32_e32 v105, v0
	v_mov_b32_e32 v106, v0
	v_mov_b32_e32 v107, v0
	v_mov_b32_e32 v108, v0
	v_mov_b32_e32 v109, v0
	v_mov_b32_e32 v110, v0
	v_mov_b32_e32 v111, v0
	v_mov_b32_e32 v144, v0
	v_mov_b32_e32 v145, v0
	v_mov_b32_e32 v146, v0
	v_mov_b32_e32 v147, v0
	v_mov_b32_e32 v148, v0
	v_mov_b32_e32 v149, v0
	v_mov_b32_e32 v150, v0
	v_mov_b32_e32 v151, v0

; template <class Epi>
; __device__ __forceinline__ void gemm_phase(LAS unsigned char* lds, const Gemm g, const StaticOrder& S, const Epi& E) {
;     ...
;         const char* nA = has_next ? (const char*)g.A + (size_t)nxt.pm * tstepA + (size_t)(nxt.pn >> g.gshift) * g.gstride : cA;
;         const char* nB = has_next ? (const char*)g.Bt + (size_t)nxt.pn * tstepB : cB;
;     ...
; #pragma unroll
;         for (int a = 0; a < 2; ++a)
; #pragma unroll
;             for (int b = 0; b < 2; ++b)
; #pragma unroll
;                 for (int m = 0; m < 4; ++m)
; #pragma unroll
;                     for (int n = 0; n < 2; ++n) acc[a][b][m][n] = (f32x4){0.f, 0.f, 0.f, 0.f};
;         cur = nxt; cA = nA; cB = nB; ++ui;
.LBB0_859:
	s_add_u32 s0, s58, 0x8000
	v_mov_b32_e32 v0, 0
	s_addc_u32 s1, s59, 0
	s_mov_b32 s69, -2
	v_mov_b32_e32 v1, v0
	v_mov_b32_e32 v2, v0
	v_mov_b32_e32 v3, v0
	s_waitcnt vmcnt(16)
	v_mov_b32_e32 v4, v0
	v_mov_b32_e32 v5, v0
	v_mov_b32_e32 v6, v0
	v_mov_b32_e32 v7, v0
	v_mov_b32_e32 v16, v0
	v_mov_b32_e32 v17, v0
	v_mov_b32_e32 v18, v0
	v_mov_b32_e32 v19, v0
	v_mov_b32_e32 v20, v0
	v_mov_b32_e32 v21, v0
	v_mov_b32_e32 v22, v0
	v_mov_b32_e32 v23, v0
	v_mov_b32_e32 v32, v0
	v_mov_b32_e32 v33, v0
	v_mov_b32_e32 v34, v0
	v_mov_b32_e32 v35, v0
	v_mov_b32_e32 v36, v0
	v_mov_b32_e32 v37, v0
	v_mov_b32_e32 v38, v0
	v_mov_b32_e32 v39, v0
	v_mov_b32_e32 v48, v0
	v_mov_b32_e32 v49, v0
	v_mov_b32_e32 v50, v0
	v_mov_b32_e32 v51, v0
	v_mov_b32_e32 v52, v0
	v_mov_b32_e32 v53, v0
	v_mov_b32_e32 v54, v0
	v_mov_b32_e32 v55, v0
	v_mov_b32_e32 v8, v0
	v_mov_b32_e32 v9, v0
	v_mov_b32_e32 v10, v0
	v_mov_b32_e32 v11, v0
	v_mov_b32_e32 v12, v0
	v_mov_b32_e32 v13, v0
	v_mov_b32_e32 v14, v0
	v_mov_b32_e32 v15, v0
	v_mov_b32_e32 v24, v0
	v_mov_b32_e32 v25, v0
	v_mov_b32_e32 v26, v0
	v_mov_b32_e32 v27, v0
	v_mov_b32_e32 v28, v0
	v_mov_b32_e32 v29, v0
	v_mov_b32_e32 v30, v0
	v_mov_b32_e32 v31, v0
	v_mov_b32_e32 v40, v0
	v_mov_b32_e32 v41, v0
	v_mov_b32_e32 v42, v0
	v_mov_b32_e32 v43, v0
	v_mov_b32_e32 v44, v0
	v_mov_b32_e32 v45, v0
	v_mov_b32_e32 v46, v0
	v_mov_b32_e32 v47, v0
	v_mov_b32_e32 v56, v0
	v_mov_b32_e32 v57, v0
	v_mov_b32_e32 v58, v0
	v_mov_b32_e32 v59, v0
	v_mov_b32_e32 v60, v0
	v_mov_b32_e32 v61, v0
	v_mov_b32_e32 v62, v0
	v_mov_b32_e32 v63, v0
	v_mov_b32_e32 v64, v0
	v_mov_b32_e32 v65, v0
	v_mov_b32_e32 v66, v0
	v_mov_b32_e32 v67, v0
	v_mov_b32_e32 v68, v0
	v_mov_b32_e32 v69, v0
	v_mov_b32_e32 v70, v0
	v_mov_b32_e32 v71, v0
	v_mov_b32_e32 v80, v0
	v_mov_b32_e32 v81, v0
	v_mov_b32_e32 v82, v0
	v_mov_b32_e32 v83, v0
	v_mov_b32_e32 v84, v0
	v_mov_b32_e32 v85, v0
	v_mov_b32_e32 v86, v0
	v_mov_b32_e32 v87, v0
	v_mov_b32_e32 v96, v0
	v_mov_b32_e32 v97, v0
	v_mov_b32_e32 v98, v0
	v_mov_b32_e32 v99, v0
	v_mov_b32_e32 v100, v0
	v_mov_b32_e32 v101, v0
	v_mov_b32_e32 v102, v0
	v_mov_b32_e32 v103, v0
	v_mov_b32_e32 v112, v0
	v_mov_b32_e32 v113, v0
	v_mov_b32_e32 v114, v0
	v_mov_b32_e32 v115, v0
	v_mov_b32_e32 v116, v0
	v_mov_b32_e32 v117, v0
	v_mov_b32_e32 v118, v0
	v_mov_b32_e32 v119, v0
	v_mov_b32_e32 v72, v0
	v_mov_b32_e32 v73, v0
	v_mov_b32_e32 v74, v0
	v_mov_b32_e32 v75, v0
	v_mov_b32_e32 v76, v0
	v_mov_b32_e32 v77, v0
	v_mov_b32_e32 v78, v0
	v_mov_b32_e32 v79, v0
	v_mov_b32_e32 v88, v0
	v_mov_b32_e32 v89, v0
	v_mov_b32_e32 v90, v0
	v_mov_b32_e32 v91, v0
	v_mov_b32_e32 v92, v0
	v_mov_b32_e32 v93, v0
	v_mov_b32_e32 v94, v0
	v_mov_b32_e32 v95, v0
	v_mov_b32_e32 v104, v0
	v_mov_b32_e32 v105, v0
	v_mov_b32_e32 v106, v0
	v_mov_b32_e32 v107, v0
	v_mov_b32_e32 v108, v0
	v_mov_b32_e32 v109, v0
	v_mov_b32_e32 v110, v0
	v_mov_b32_e32 v111, v0
	v_mov_b32_e32 v144, v0
	v_mov_b32_e32 v145, v0
	v_mov_b32_e32 v146, v0
	v_mov_b32_e32 v147, v0
	v_mov_b32_e32 v148, v0
	v_mov_b32_e32 v149, v0
	v_mov_b32_e32 v150, v0
	v_mov_b32_e32 v151, v0
